# attention lazy rescale: alpha exp and l*alpha moved into the rare rescale block; common path l += psum
# speedup vs baseline: 1.0041x; 1.0041x over previous
.LBB0_326:
	v_add_f32_e32 v0, 0, v0
	v_add_f32_e32 v0, v14, v0
	v_add_f32_e32 v0, v232, v0
	v_add_f32_e32 v0, v236, v0
	v_add_f32_e32 v0, v237, v0
	v_add_f32_e32 v0, v238, v0
	v_add_f32_e32 v0, v239, v0
	v_add_f32_e32 v0, v240, v0
	v_add_f32_e32 v0, v241, v0
	v_add_f32_e32 v0, v242, v0
	v_add_f32_e32 v0, v243, v0
	v_add_f32_e32 v0, v244, v0
	v_add_f32_e32 v0, v245, v0
	v_add_f32_e32 v0, v246, v0
	v_sub_f32_e32 v10, v231, v234
	v_add_f32_e32 v0, v247, v0
	v_add_f32_e32 v232, v248, v0
	v_add_u32_e32 v231, 0x1000, v230
	s_add_i32 s0, s64, -7
	s_cmp_ge_i32 s0, s56
	s_mov_b64 vcc, s[98:99]
	s_cbranch_vccz .Lrse_0
	v_exp_f32_e32 v0, v10
	s_nop 0
	v_fmac_f32_e32 v232, v233, v0
	v_mul_f32_e32 v78, v0, v78
	v_mul_f32_e32 v79, v0, v79
	v_mul_f32_e32 v76, v0, v76
	v_mul_f32_e32 v77, v0, v77
	v_mul_f32_e32 v74, v0, v74
	v_mul_f32_e32 v75, v0, v75
	v_mul_f32_e32 v72, v0, v72
	v_mul_f32_e32 v73, v0, v73
	v_mul_f32_e32 v70, v0, v70
	v_mul_f32_e32 v71, v0, v71
	v_mul_f32_e32 v68, v0, v68
	v_mul_f32_e32 v69, v0, v69
	v_mul_f32_e32 v66, v0, v66
	v_mul_f32_e32 v67, v0, v67
	v_mul_f32_e32 v64, v0, v64
	v_mul_f32_e32 v65, v0, v65
	v_mul_f32_e32 v62, v0, v62
	v_mul_f32_e32 v63, v0, v63
	v_mul_f32_e32 v60, v0, v60
	v_mul_f32_e32 v61, v0, v61
	v_mul_f32_e32 v58, v0, v58
	v_mul_f32_e32 v59, v0, v59
	v_mul_f32_e32 v56, v0, v56
	v_mul_f32_e32 v57, v0, v57
	v_mul_f32_e32 v54, v0, v54
	v_mul_f32_e32 v55, v0, v55
	v_mul_f32_e32 v52, v0, v52
	v_mul_f32_e32 v53, v0, v53
	v_mul_f32_e32 v50, v0, v50
	v_mul_f32_e32 v51, v0, v51
	v_mul_f32_e32 v48, v0, v48
	v_mul_f32_e32 v49, v0, v49
	s_branch .Lrs_0
.Lrse_0:
	v_add_f32_e32 v232, v233, v232
.Lrs_0:
	v_max3_f32 v0, v80, s18, v81
	v_max3_f32 v0, v0, v82, v83
	v_max3_f32 v0, v0, v84, v85
	v_max3_f32 v0, v0, v86, v87
	v_max3_f32 v0, v0, v88, v89
	v_max3_f32 v0, v0, v90, v91
	v_max3_f32 v0, v0, v92, v93
	v_max3_f32 v0, v0, v94, v95
	v_mov_b32_e32 v10, v0
	v_mov_b32_e32 v255, v0
	s_nop 1
	v_permlane32_swap_b32_e32 v10, v255
	s_waitcnt lgkmcnt(0)
	v_max3_f32 v14, v235, v10, v255
	v_sub_f32_e32 v255, v14, v235
	v_cmp_lt_f32_e64 s[98:99], 4.0, v255
	s_nop 1
	v_cndmask_b32_e64 v14, v235, v14, s[98:99]
	v_sub_f32_e32 v0, v80, v14
	v_exp_f32_e32 v11, v0
	v_sub_f32_e32 v12, v81, v14
	v_exp_f32_e32 v12, v12
	v_sub_f32_e32 v13, v82, v14
	v_exp_f32_e32 v13, v13
	v_sub_f32_e32 v80, v83, v14
	v_exp_f32_e32 v81, v80
	v_sub_f32_e32 v80, v84, v14
	v_add_f32_e32 v0, 0, v11
	v_exp_f32_e32 v82, v80
	v_sub_f32_e32 v80, v85, v14
	v_add_f32_e32 v0, v12, v0
	v_exp_f32_e32 v83, v80
	v_sub_f32_e32 v80, v86, v14
	v_add_f32_e32 v0, v13, v0
	v_exp_f32_e32 v84, v80
	v_sub_f32_e32 v80, v87, v14
	v_add_f32_e32 v0, v81, v0
	v_exp_f32_e32 v85, v80
	v_sub_f32_e32 v80, v88, v14
	v_add_f32_e32 v0, v82, v0
	v_exp_f32_e32 v86, v80
	v_sub_f32_e32 v80, v89, v14
	v_add_f32_e32 v0, v83, v0
	v_exp_f32_e32 v87, v80
	v_sub_f32_e32 v80, v90, v14
	v_add_f32_e32 v0, v84, v0
	v_exp_f32_e32 v88, v80
	v_sub_f32_e32 v80, v91, v14
	v_add_f32_e32 v0, v85, v0
	v_exp_f32_e32 v89, v80
	v_sub_f32_e32 v80, v92, v14
	v_add_f32_e32 v0, v86, v0
	v_exp_f32_e32 v90, v80
	v_sub_f32_e32 v80, v93, v14
	v_add_f32_e32 v0, v87, v0
	v_exp_f32_e32 v91, v80
	v_sub_f32_e32 v80, v94, v14
	v_add_f32_e32 v0, v88, v0
	v_exp_f32_e32 v92, v80
	v_sub_f32_e32 v80, v95, v14
	v_sub_f32_e32 v10, v235, v14
	v_add_f32_e32 v0, v89, v0
	v_exp_f32_e32 v93, v80
	v_add_f32_e32 v0, v90, v0
	v_add_f32_e32 v0, v91, v0
	v_add_f32_e32 v0, v92, v0
	v_add_f32_e32 v0, v93, v0
	s_mov_b64 vcc, s[98:99]
	s_cbranch_vccz .Lrse_1
	v_exp_f32_e32 v10, v10
	s_nop 0
	v_fmac_f32_e32 v0, v15, v10
	v_mul_f32_e32 v46, v10, v46
	v_mul_f32_e32 v47, v10, v47
	v_mul_f32_e32 v44, v10, v44
	v_mul_f32_e32 v45, v10, v45
	v_mul_f32_e32 v42, v10, v42
	v_mul_f32_e32 v43, v10, v43
	v_mul_f32_e32 v40, v10, v40
	v_mul_f32_e32 v41, v10, v41
	v_mul_f32_e32 v38, v10, v38
	v_mul_f32_e32 v39, v10, v39
	v_mul_f32_e32 v36, v10, v36
	v_mul_f32_e32 v37, v10, v37
	v_mul_f32_e32 v34, v10, v34
	v_mul_f32_e32 v35, v10, v35
	v_mul_f32_e32 v32, v10, v32
	v_mul_f32_e32 v33, v10, v33
	v_mul_f32_e32 v30, v10, v30
	v_mul_f32_e32 v31, v10, v31
	v_mul_f32_e32 v28, v10, v28
	v_mul_f32_e32 v29, v10, v29
	v_mul_f32_e32 v26, v10, v26
	v_mul_f32_e32 v27, v10, v27
	v_mul_f32_e32 v24, v10, v24
	v_mul_f32_e32 v25, v10, v25
	v_mul_f32_e32 v22, v10, v22
	v_mul_f32_e32 v23, v10, v23
	v_mul_f32_e32 v20, v10, v20
	v_mul_f32_e32 v21, v10, v21
	v_mul_f32_e32 v18, v10, v18
	v_mul_f32_e32 v19, v10, v19
	v_mul_f32_e32 v16, v10, v16
	v_mul_f32_e32 v17, v10, v17
	s_branch .Lrs_1
.Lrse_1:
	v_add_f32_e32 v0, v15, v0

.LBB0_347:
	v_add_f32_e32 v11, 0, v235
	v_add_f32_e32 v11, v236, v11
	v_add_f32_e32 v11, v237, v11
	v_add_f32_e32 v11, v238, v11
	v_add_f32_e32 v11, v239, v11
	v_add_f32_e32 v11, v240, v11
	v_add_f32_e32 v11, v241, v11
	v_add_f32_e32 v11, v242, v11
	v_add_f32_e32 v11, v243, v11
	v_add_f32_e32 v11, v244, v11
	v_add_f32_e32 v11, v245, v11
	v_sub_f32_e32 v10, v234, v233
	v_add_f32_e32 v11, v246, v11
	v_add_f32_e32 v11, v247, v11
	v_add_f32_e32 v11, v248, v11
	v_add_f32_e32 v11, v249, v11
	v_add_f32_e32 v160, v250, v11
	s_mov_b64 vcc, s[98:99]
	s_cbranch_vccz .Lrse_2
	v_exp_f32_e32 v10, v10
	s_nop 0
	v_fmac_f32_e32 v160, v232, v10
	v_mul_f32_e32 v78, v10, v78
	v_mul_f32_e32 v79, v10, v79
	v_mul_f32_e32 v76, v10, v76
	v_mul_f32_e32 v77, v10, v77
	v_mul_f32_e32 v74, v10, v74
	v_mul_f32_e32 v75, v10, v75
	v_mul_f32_e32 v72, v10, v72
	v_mul_f32_e32 v73, v10, v73
	v_mul_f32_e32 v70, v10, v70
	v_mul_f32_e32 v71, v10, v71
	v_mul_f32_e32 v68, v10, v68
	v_mul_f32_e32 v69, v10, v69
	v_mul_f32_e32 v66, v10, v66
	v_mul_f32_e32 v67, v10, v67
	v_mul_f32_e32 v64, v10, v64
	v_mul_f32_e32 v65, v10, v65
	v_mul_f32_e32 v62, v10, v62
	v_mul_f32_e32 v63, v10, v63
	v_mul_f32_e32 v60, v10, v60
	v_mul_f32_e32 v61, v10, v61
	v_mul_f32_e32 v58, v10, v58
	v_mul_f32_e32 v59, v10, v59
	v_mul_f32_e32 v56, v10, v56
	v_mul_f32_e32 v57, v10, v57
	v_mul_f32_e32 v54, v10, v54
	v_mul_f32_e32 v55, v10, v55
	v_mul_f32_e32 v52, v10, v52
	v_mul_f32_e32 v53, v10, v53
	v_mul_f32_e32 v50, v10, v50
	v_mul_f32_e32 v51, v10, v51
	v_mul_f32_e32 v48, v10, v48
	v_mul_f32_e32 v49, v10, v49
	s_branch .Lrs_2
.Lrse_2:
	v_add_f32_e32 v160, v232, v160
.Lrs_2:
	v_max3_f32 v10, v80, s18, v81
	v_max3_f32 v10, v10, v82, v83
	v_max3_f32 v10, v10, v84, v85
	v_max3_f32 v10, v10, v86, v87
	v_max3_f32 v10, v10, v88, v89
	v_max3_f32 v10, v10, v90, v91
	v_max3_f32 v10, v10, v92, v93
	v_max3_f32 v10, v10, v94, v95
	v_mov_b32_e32 v11, v10
	v_mov_b32_e32 v255, v10
	s_nop 1
	v_permlane32_swap_b32_e32 v11, v255
	v_mov_b32_e32 v232, v160
	s_waitcnt lgkmcnt(0)
	v_max3_f32 v161, v14, v11, v255
	v_sub_f32_e32 v255, v161, v14
	v_cmp_lt_f32_e64 s[98:99], 4.0, v255
	s_nop 1
	v_cndmask_b32_e64 v161, v14, v161, s[98:99]
	v_sub_f32_e32 v11, v80, v161
	v_exp_f32_e32 v11, v11
	v_sub_f32_e32 v13, v81, v161
	v_sub_f32_e32 v10, v14, v161
	v_exp_f32_e32 v13, v13
	v_sub_f32_e32 v14, v82, v161
	v_exp_f32_e32 v14, v14
	v_sub_f32_e32 v80, v83, v161
	v_exp_f32_e32 v81, v80
	v_sub_f32_e32 v80, v84, v161
	v_add_f32_e32 v12, 0, v11
	v_exp_f32_e32 v82, v80
	v_sub_f32_e32 v80, v85, v161
	v_add_f32_e32 v12, v13, v12
	v_exp_f32_e32 v83, v80
	v_sub_f32_e32 v80, v86, v161
	v_add_f32_e32 v12, v14, v12
	v_exp_f32_e32 v85, v80
	v_sub_f32_e32 v80, v87, v161
	v_add_f32_e32 v12, v81, v12
	v_exp_f32_e32 v86, v80
	v_sub_f32_e32 v80, v88, v161
	v_add_f32_e32 v12, v82, v12
	v_exp_f32_e32 v87, v80
	v_sub_f32_e32 v80, v89, v161
	v_add_f32_e32 v12, v83, v12
	v_exp_f32_e32 v88, v80
	v_sub_f32_e32 v80, v90, v161
	v_add_f32_e32 v12, v85, v12
	v_exp_f32_e32 v89, v80
	v_sub_f32_e32 v80, v91, v161
	v_add_f32_e32 v12, v86, v12
	v_exp_f32_e32 v90, v80
	v_sub_f32_e32 v80, v92, v161
	v_add_f32_e32 v12, v87, v12
	v_exp_f32_e32 v91, v80
	v_sub_f32_e32 v80, v93, v161
	v_add_f32_e32 v12, v88, v12
	v_exp_f32_e32 v92, v80
	v_sub_f32_e32 v80, v94, v161
	v_add_f32_e32 v12, v89, v12
	v_exp_f32_e32 v93, v80
	v_sub_f32_e32 v80, v95, v161
	v_add_f32_e32 v12, v90, v12
	v_exp_f32_e32 v94, v80
	v_add_f32_e32 v12, v91, v12
	v_add_f32_e32 v12, v92, v12
	v_add_f32_e32 v12, v93, v12
	v_add_f32_e32 v84, v94, v12
	s_mov_b64 vcc, s[98:99]
	s_cbranch_vccz .Lrse_3
	v_exp_f32_e32 v10, v10
	s_nop 0
	v_fmac_f32_e32 v84, v0, v10
	v_mul_f32_e32 v46, v10, v46
	v_mul_f32_e32 v47, v10, v47
	v_mul_f32_e32 v44, v10, v44
	v_mul_f32_e32 v45, v10, v45
	v_mul_f32_e32 v42, v10, v42
	v_mul_f32_e32 v43, v10, v43
	v_mul_f32_e32 v40, v10, v40
	v_mul_f32_e32 v41, v10, v41
	v_mul_f32_e32 v38, v10, v38
	v_mul_f32_e32 v39, v10, v39
	v_mul_f32_e32 v36, v10, v36
	v_mul_f32_e32 v37, v10, v37
	v_mul_f32_e32 v34, v10, v34
	v_mul_f32_e32 v35, v10, v35
	v_mul_f32_e32 v32, v10, v32
	v_mul_f32_e32 v33, v10, v33
	v_mul_f32_e32 v30, v10, v30
	v_mul_f32_e32 v31, v10, v31
	v_mul_f32_e32 v28, v10, v28
	v_mul_f32_e32 v29, v10, v29
	v_mul_f32_e32 v26, v10, v26
	v_mul_f32_e32 v27, v10, v27
	v_mul_f32_e32 v24, v10, v24
	v_mul_f32_e32 v25, v10, v25
	v_mul_f32_e32 v22, v10, v22
	v_mul_f32_e32 v23, v10, v23
	v_mul_f32_e32 v20, v10, v20
	v_mul_f32_e32 v21, v10, v21
	v_mul_f32_e32 v18, v10, v18
	v_mul_f32_e32 v19, v10, v19
	v_mul_f32_e32 v16, v10, v16
	v_mul_f32_e32 v17, v10, v17
	s_branch .Lrs_3
.Lrse_3:
	v_add_f32_e32 v84, v0, v84
.Lrs_3:
	v_add_u32_e32 v0, 0x3800, v230
	v_cvt_pk_bf16_f32 v80, v11, v13
	v_cvt_pk_bf16_f32 v82, v82, v83
	v_cvt_pk_bf16_f32 v83, v85, v86
	v_cvt_pk_bf16_f32 v10, v87, v88
	v_cvt_pk_bf16_f32 v11, v89, v90
	v_cvt_pk_bf16_f32 v12, v91, v92
	v_cvt_pk_bf16_f32 v13, v93, v94
	ds_read2_b64 v[86:89], v0 offset1:2
	ds_read2_b64 v[90:93], v0 offset0:4 offset1:6
	v_add_u32_e32 v0, 0x4000, v230
	v_cvt_pk_bf16_f32 v81, v14, v81
	s_waitcnt lgkmcnt(1)
	v_mfma_f32_32x32x16_bf16 v[64:79], v[86:89], v[6:9], v[64:79]
	v_mov_b32_e32 v14, v161
	v_mfma_f32_32x32x16_bf16 v[32:47], v[86:89], v[80:83], v[32:47]
	ds_read2_b64 v[86:89], v0 offset0:64 offset1:66
	s_waitcnt lgkmcnt(0)
	v_mfma_f32_32x32x16_bf16 v[48:63], v[86:89], v[6:9], v[48:63]
	ds_read2_b64 v[6:9], v0 offset0:68 offset1:70
	v_mov_b32_e32 v0, v84
	s_waitcnt lgkmcnt(0)
	s_barrier
	v_mfma_f32_32x32x16_bf16 v[16:31], v[86:89], v[80:83], v[16:31]
	v_mfma_f32_32x32x16_bf16 v[64:79], v[90:93], v[2:5], v[64:79]
	v_mfma_f32_32x32x16_bf16 v[32:47], v[90:93], v[10:13], v[32:47]
	v_mfma_f32_32x32x16_bf16 v[48:63], v[6:9], v[2:5], v[48:63]
	v_mfma_f32_32x32x16_bf16 v[16:31], v[6:9], v[10:13], v[16:31]
	s_add_i32 s0, s64, -6
	s_cmp_ge_i32 s0, s56
	s_cbranch_scc1 .LBB0_331

.LBB0_365:
	v_add_f32_e32 v11, 0, v235
	v_add_f32_e32 v11, v236, v11
	v_add_f32_e32 v11, v237, v11
	v_add_f32_e32 v11, v238, v11
	v_add_f32_e32 v11, v239, v11
	v_add_f32_e32 v11, v240, v11
	v_add_f32_e32 v11, v241, v11
	v_add_f32_e32 v11, v242, v11
	v_add_f32_e32 v11, v243, v11
	v_add_f32_e32 v11, v244, v11
	v_add_f32_e32 v11, v245, v11
	v_sub_f32_e32 v10, v233, v234
	v_add_f32_e32 v11, v246, v11
	v_add_f32_e32 v11, v247, v11
	v_add_f32_e32 v11, v248, v11
	v_add_f32_e32 v11, v249, v11
	v_add_f32_e32 v160, v250, v11
	s_mov_b64 vcc, s[98:99]
	s_cbranch_vccz .Lrse_4
	v_exp_f32_e32 v10, v10
	s_nop 0
	v_fmac_f32_e32 v160, v232, v10
	v_mul_f32_e32 v78, v10, v78
	v_mul_f32_e32 v79, v10, v79
	v_mul_f32_e32 v76, v10, v76
	v_mul_f32_e32 v77, v10, v77
	v_mul_f32_e32 v74, v10, v74
	v_mul_f32_e32 v75, v10, v75
	v_mul_f32_e32 v72, v10, v72
	v_mul_f32_e32 v73, v10, v73
	v_mul_f32_e32 v70, v10, v70
	v_mul_f32_e32 v71, v10, v71
	v_mul_f32_e32 v68, v10, v68
	v_mul_f32_e32 v69, v10, v69
	v_mul_f32_e32 v66, v10, v66
	v_mul_f32_e32 v67, v10, v67
	v_mul_f32_e32 v64, v10, v64
	v_mul_f32_e32 v65, v10, v65
	v_mul_f32_e32 v62, v10, v62
	v_mul_f32_e32 v63, v10, v63
	v_mul_f32_e32 v60, v10, v60
	v_mul_f32_e32 v61, v10, v61
	v_mul_f32_e32 v58, v10, v58
	v_mul_f32_e32 v59, v10, v59
	v_mul_f32_e32 v56, v10, v56
	v_mul_f32_e32 v57, v10, v57
	v_mul_f32_e32 v54, v10, v54
	v_mul_f32_e32 v55, v10, v55
	v_mul_f32_e32 v52, v10, v52
	v_mul_f32_e32 v53, v10, v53
	v_mul_f32_e32 v50, v10, v50
	v_mul_f32_e32 v51, v10, v51
	v_mul_f32_e32 v48, v10, v48
	v_mul_f32_e32 v49, v10, v49
	s_branch .Lrs_4

.LBB0_381:
	v_add_f32_e32 v11, 0, v15
	v_add_f32_e32 v11, v233, v11
	v_add_f32_e32 v11, v235, v11
	v_add_f32_e32 v11, v236, v11
	v_add_f32_e32 v11, v237, v11
	v_add_f32_e32 v11, v238, v11
	v_add_f32_e32 v11, v239, v11
	v_add_f32_e32 v11, v240, v11
	v_add_f32_e32 v11, v241, v11
	v_add_f32_e32 v11, v242, v11
	v_add_f32_e32 v11, v243, v11
	v_sub_f32_e32 v10, v234, v231
	v_add_f32_e32 v11, v244, v11
	v_add_f32_e32 v11, v245, v11
	v_add_f32_e32 v11, v246, v11
	v_add_f32_e32 v11, v247, v11
	v_add_f32_e32 v233, v248, v11
	s_mov_b64 vcc, s[98:99]
	s_cbranch_vccz .Lrse_6
	v_exp_f32_e32 v10, v10
	s_nop 0
	v_fmac_f32_e32 v233, v232, v10
	v_mul_f32_e32 v78, v10, v78
	v_mul_f32_e32 v79, v10, v79
	v_mul_f32_e32 v76, v10, v76
	v_mul_f32_e32 v77, v10, v77
	v_mul_f32_e32 v74, v10, v74
	v_mul_f32_e32 v75, v10, v75
	v_mul_f32_e32 v72, v10, v72
	v_mul_f32_e32 v73, v10, v73
	v_mul_f32_e32 v70, v10, v70
	v_mul_f32_e32 v71, v10, v71
	v_mul_f32_e32 v68, v10, v68
	v_mul_f32_e32 v69, v10, v69
	v_mul_f32_e32 v66, v10, v66
	v_mul_f32_e32 v67, v10, v67
	v_mul_f32_e32 v64, v10, v64
	v_mul_f32_e32 v65, v10, v65
	v_mul_f32_e32 v62, v10, v62
	v_mul_f32_e32 v63, v10, v63
	v_mul_f32_e32 v60, v10, v60
	v_mul_f32_e32 v61, v10, v61
	v_mul_f32_e32 v58, v10, v58
	v_mul_f32_e32 v59, v10, v59
	v_mul_f32_e32 v56, v10, v56
	v_mul_f32_e32 v57, v10, v57
	v_mul_f32_e32 v54, v10, v54
	v_mul_f32_e32 v55, v10, v55
	v_mul_f32_e32 v52, v10, v52
	v_mul_f32_e32 v53, v10, v53
	v_mul_f32_e32 v50, v10, v50
	v_mul_f32_e32 v51, v10, v51
	v_mul_f32_e32 v48, v10, v48
	v_mul_f32_e32 v49, v10, v49
	s_branch .Lrs_6
.Lrse_6:
	v_add_f32_e32 v233, v232, v233
.Lrs_6:
	v_max3_f32 v10, v80, s18, v81
	v_max3_f32 v10, v10, v82, v83
	v_max3_f32 v10, v10, v84, v85
	v_max3_f32 v10, v10, v86, v87
	v_max3_f32 v10, v10, v88, v89
	v_max3_f32 v10, v10, v90, v91
	v_max3_f32 v10, v10, v92, v93
	v_max3_f32 v10, v10, v94, v95
	v_mov_b32_e32 v11, v10
	v_mov_b32_e32 v255, v10
	s_nop 1
	v_permlane32_swap_b32_e32 v11, v255
	s_waitcnt lgkmcnt(0)
	v_max3_f32 v235, v14, v11, v255
	v_sub_f32_e32 v255, v235, v14
	v_cmp_lt_f32_e64 s[98:99], 4.0, v255
	s_nop 1
	v_cndmask_b32_e64 v235, v14, v235, s[98:99]
	v_sub_f32_e32 v11, v80, v235
	v_exp_f32_e32 v11, v11
	v_sub_f32_e32 v13, v81, v235
	v_sub_f32_e32 v10, v14, v235
	v_exp_f32_e32 v13, v13
	v_sub_f32_e32 v14, v82, v235
	v_exp_f32_e32 v14, v14
	v_sub_f32_e32 v15, v83, v235
	v_exp_f32_e32 v81, v15
	v_sub_f32_e32 v15, v84, v235
	v_add_f32_e32 v12, 0, v11
	v_exp_f32_e32 v82, v15
	v_sub_f32_e32 v15, v85, v235
	v_add_f32_e32 v12, v13, v12
	v_exp_f32_e32 v83, v15
	v_sub_f32_e32 v15, v86, v235
	v_add_f32_e32 v12, v14, v12
	v_exp_f32_e32 v84, v15
	v_sub_f32_e32 v15, v87, v235
	v_add_f32_e32 v12, v81, v12
	v_exp_f32_e32 v85, v15
	v_sub_f32_e32 v15, v88, v235
	v_add_f32_e32 v12, v82, v12
	v_exp_f32_e32 v86, v15
	v_sub_f32_e32 v15, v89, v235
	v_add_f32_e32 v12, v83, v12
	v_exp_f32_e32 v87, v15
	v_sub_f32_e32 v15, v90, v235
	v_add_f32_e32 v12, v84, v12
	v_exp_f32_e32 v88, v15
	v_sub_f32_e32 v15, v91, v235
	v_add_f32_e32 v12, v85, v12
	v_exp_f32_e32 v89, v15
	v_sub_f32_e32 v15, v92, v235
	v_add_f32_e32 v12, v86, v12
	v_exp_f32_e32 v90, v15
	v_sub_f32_e32 v15, v93, v235
	v_add_f32_e32 v12, v87, v12
	v_exp_f32_e32 v91, v15
	v_sub_f32_e32 v15, v94, v235
	v_add_f32_e32 v12, v88, v12
	v_exp_f32_e32 v92, v15
	v_sub_f32_e32 v15, v95, v235
	v_add_f32_e32 v12, v89, v12
	v_exp_f32_e32 v93, v15
	v_add_f32_e32 v12, v90, v12
	v_add_f32_e32 v12, v91, v12
	v_add_f32_e32 v12, v92, v12
	v_add_f32_e32 v15, v93, v12
	s_mov_b64 vcc, s[98:99]
	s_cbranch_vccz .Lrse_7
	v_exp_f32_e32 v10, v10
	s_nop 0
	v_fmac_f32_e32 v15, v0, v10
	v_mul_f32_e32 v46, v10, v46
	v_mul_f32_e32 v47, v10, v47
	v_mul_f32_e32 v44, v10, v44
	v_mul_f32_e32 v45, v10, v45
	v_mul_f32_e32 v42, v10, v42
	v_mul_f32_e32 v43, v10, v43
	v_mul_f32_e32 v40, v10, v40
	v_mul_f32_e32 v41, v10, v41
	v_mul_f32_e32 v38, v10, v38
	v_mul_f32_e32 v39, v10, v39
	v_mul_f32_e32 v36, v10, v36
	v_mul_f32_e32 v37, v10, v37
	v_mul_f32_e32 v34, v10, v34
	v_mul_f32_e32 v35, v10, v35
	v_mul_f32_e32 v32, v10, v32
	v_mul_f32_e32 v33, v10, v33
	v_mul_f32_e32 v30, v10, v30
	v_mul_f32_e32 v31, v10, v31
	v_mul_f32_e32 v28, v10, v28
	v_mul_f32_e32 v29, v10, v29
	v_mul_f32_e32 v26, v10, v26
	v_mul_f32_e32 v27, v10, v27
	v_mul_f32_e32 v24, v10, v24
	v_mul_f32_e32 v25, v10, v25
	v_mul_f32_e32 v22, v10, v22
	v_mul_f32_e32 v23, v10, v23
	v_mul_f32_e32 v20, v10, v20
	v_mul_f32_e32 v21, v10, v21
	v_mul_f32_e32 v18, v10, v18
	v_mul_f32_e32 v19, v10, v19
	v_mul_f32_e32 v16, v10, v16
	v_mul_f32_e32 v17, v10, v17
	s_branch .Lrs_7
.Lrse_7:
	v_add_f32_e32 v15, v0, v15
.Lrs_7:
	v_add_u32_e32 v0, 0x3800, v230
	v_cvt_pk_bf16_f32 v80, v11, v13
	v_cvt_pk_bf16_f32 v82, v82, v83
	v_cvt_pk_bf16_f32 v83, v84, v85
	v_cvt_pk_bf16_f32 v10, v86, v87
	v_cvt_pk_bf16_f32 v11, v88, v89
	v_cvt_pk_bf16_f32 v12, v90, v91
	ds_read2_b64 v[84:87], v0 offset1:2
	ds_read2_b64 v[88:91], v0 offset0:4 offset1:6
	v_add_u32_e32 v0, 0x4000, v230
	v_cvt_pk_bf16_f32 v81, v14, v81
	s_waitcnt lgkmcnt(1)
	v_mfma_f32_32x32x16_bf16 v[64:79], v[84:87], v[6:9], v[64:79]
	v_cvt_pk_bf16_f32 v13, v92, v93
	v_mfma_f32_32x32x16_bf16 v[32:47], v[84:87], v[80:83], v[32:47]
	ds_read2_b64 v[84:87], v0 offset0:64 offset1:66
	s_waitcnt lgkmcnt(0)
	v_mfma_f32_32x32x16_bf16 v[48:63], v[84:87], v[6:9], v[48:63]
	ds_read2_b64 v[6:9], v0 offset0:68 offset1:70
	s_waitcnt lgkmcnt(0)
	s_barrier
	v_mfma_f32_32x32x16_bf16 v[16:31], v[84:87], v[80:83], v[16:31]
	v_mfma_f32_32x32x16_bf16 v[64:79], v[88:91], v[2:5], v[64:79]
	v_mfma_f32_32x32x16_bf16 v[32:47], v[88:91], v[10:13], v[32:47]
	v_mfma_f32_32x32x16_bf16 v[48:63], v[6:9], v[2:5], v[48:63]
	v_mfma_f32_32x32x16_bf16 v[16:31], v[6:9], v[10:13], v[16:31]
